# a+b plus B-h1 register double-buffer in P1 K-loop: 12/12/12/12 ds_reads and 4/4/4/4 DMAs per sub-phase using 16 spare VGPRs
# baseline (speedup 1.0000x reference)
;     __device__ bool next(int i, Unit& u) const { if (i > 1) return false; const int xcd = c & 7, idx = c >> 3; u.pm = 16 * i + 4 * (xcd >> 1) + (idx & 3); u.pn = 8 * (xcd & 1) + (idx >> 2); return true; }
; #define PG8_STAGE(bufoff, gbase, voff) do { const char* _gb = (const char*)(gbase); asm volatile("" : "+s"(_gb)); _Pragma("unroll") for (int _i = 0; _i < 2; ++_i) { asm volatile("" : "+v"((voff)[_i])); \
;         __builtin_amdgcn_global_load_lds((const unsigned*)(_gb + (voff)[_i]), (PG8_LAS unsigned*)(lds + (bufoff) + ldsw + _i * 8192), 16, 0, 0); } } while (0)
; #define PG8_WAIT_V(n) asm volatile("s_waitcnt vmcnt(" #n ")" ::: "memory")
; #define PG8_BAR __builtin_amdgcn_s_barrier()
; #define PG8_WAIT_V(n) asm volatile("s_waitcnt vmcnt(" #n ")" ::: "memory")
; #define PG8_BAR __builtin_amdgcn_s_barrier()
; template <class Epi, class Sched, bool ALIGN_EPI = false, bool SP2 = false>
; __device__ __forceinline__ void gemm_phase(PG8_LAS unsigned char* lds, const Gemm g, const Sched& S, const Epi& E) {
;     ...
;     const int aoff = lds_byte(wr * 64 + fr, fq * 8), boff = lds_byte(wc * 32 + fr, fq * 8);
;     ...
;     Unit cur, nxt; int ui = 0;
;     if (!S.next(0, cur)) return;
;     f32x4 acc[2][2][4][2];
; #pragma unroll
;     for (int a = 0; a < 2; ++a)
; #pragma unroll
;         for (int b = 0; b < 2; ++b)
; #pragma unroll
;             for (int m = 0; m < 4; ++m)
; #pragma unroll
;                 for (int n = 0; n < 2; ++n) acc[a][b][m][n] = (f32x4){0.f, 0.f, 0.f, 0.f};
;     bf16x8 At[4][2], B0[2][2], B1[2][2];
;     const char* cA = (const char*)g.A + (size_t)cur.pm * tstep; const char* cB = (const char*)g.Bt + (size_t)cur.pn * tstep;
;     S.a_ready(cur);
;     if constexpr (SP2) {
;         PG8_STAGE(PG8_SB(0, 0), cB, voffB); PG8_STAGE(PG8_SB(0, 1), cB + hstep, voffB); PG8_STAGE(PG8_SA(0, 0), cA, voffA); PG8_STAGE(PG8_SA(0, 1), cA + hstep, voffA);
;         if (wr == 1) PG8_BAR;
;         PG8_WAIT_V(2); PG8_BAR;
;         PG8_STAGE(PG8_SB(1, 0), cB + kstep, voffB); PG8_STAGE(PG8_SA(1, 0), cA + kstep, voffA); PG8_STAGE(PG8_SB(1, 1), cB + hstep + kstep, voffB);
;         PG8_WAIT_V(6); PG8_BAR;
; __global__ void __launch_bounds__(NWAVES * 64, 2) hyb_fwd(Args args) {
;     ...
;         pg8::EpiProj E{(bf16*)(ws + WS_GU), (bf16*)(ws + WS_GV), (bf16*)(ws + WS_XR), (bf16*)(ws + WS_GYR), (bf16*)(ws + WS_SGA), (bf16*)(ws + WS_SGB), fctl + CW_VSUM, fctl + CW_VSQ};
.LBB0_307:
	s_load_dwordx2 s[14:15], s[0:1], 0xc0
	s_waitcnt vmcnt(2)
	s_barrier
	v_bfe_u32 v4, v2, 4, 2
	v_and_b32_e32 v3, 15, v2
	s_waitcnt lgkmcnt(0)
	s_add_u32 s20, s14, 0x26800000
	s_addc_u32 s21, s15, 0
	s_add_u32 s30, s14, 0x28800000
	s_addc_u32 s31, s15, 0
	s_add_u32 s34, s14, 0x2a800000
	s_addc_u32 s35, s15, 0
	s_add_u32 s38, s14, 0x2e800000
	s_addc_u32 s39, s15, 0
	s_add_u32 s40, s14, 0x32800000
	s_addc_u32 s41, s15, 0
	s_add_u32 s52, s14, 0x36800000
	s_addc_u32 s53, s15, 0
	s_add_u32 s54, s14, 0x10000
	s_addc_u32 s55, s15, 0
	s_add_u32 s56, s14, 0x18000
	s_addc_u32 s57, s15, 0
	s_lshl_b32 s6, s6, 5
	s_and_b32 s13, s6, 0x60
	s_lshl_b32 s11, s5, 13
	s_lshl_b32 s14, s13, 7
	s_add_u32 s6, s2, 0x80
	s_addc_u32 s7, s3, 0
	s_add_i32 m0, s63, 0x18000
	v_lshlrev_b32_e32 v5, 4, v4
	global_load_lds_dwordx4 v144, s[6:7]
	s_add_i32 m0, s63, 0x1a000
	v_lshlrev_b32_e32 v2, 2, v2
	global_load_lds_dwordx4 v146, s[6:7]
	s_add_u32 s6, s8, 0x80
	s_addc_u32 s7, s9, 0
	s_add_i32 s91, s63, 0x8000
	s_mov_b32 m0, s91
	s_add_i32 s92, s63, 0xa000
	v_lshl_or_b32 v147, s5, 6, v3
	global_load_lds_dwordx4 v1, s[6:7]
	s_mov_b32 m0, s92
	v_lshl_or_b32 v3, v3, 6, v5
	global_load_lds_dwordx4 v145, s[6:7]
	s_add_u32 s6, s2, 0x100080
	s_addc_u32 s7, s3, 0
	s_add_i32 m0, s63, 0x1c000
	v_and_b32_e32 v2, 32, v2
	global_load_lds_dwordx4 v144, s[6:7]
	s_add_i32 m0, s63, 0x1e000
	s_cmpk_lt_u32 s4, 0x100
	global_load_lds_dwordx4 v146, s[6:7]
	s_waitcnt vmcnt(6)
	v_bitop3_b32 v5, v3, s11, v2 bitop3:0xde
	v_bitop3_b32 v148, v3, s14, v2 bitop3:0xde
	s_cselect_b64 s[58:59], -1, 0
	s_add_i32 s95, 0, 0x10000
	s_add_i32 s96, 0, 0x14000
	v_mbcnt_lo_u32_b32 v2, -1, 0
	v_lshl_or_b32 v149, v4, 3, s13
	v_cmp_eq_u32_e64 s[4:5], 0, v4
	s_ashr_i32 s93, s47, 31
	s_ashr_i32 s94, s46, 31
	v_mov_b64_e32 v[130:131], 0xa00
	v_mov_b64_e32 v[132:133], 0x9ff
	v_add_u32_e32 v150, s95, v148
	v_add_u32_e32 v151, s96, v148
	v_add_u32_e32 v152, 0, v5
	s_mov_b32 s60, 0xbfb8aa3b
	s_mov_b32 s62, 0x3dd2d3e8
	s_mov_b32 s64, 0xc0135761
	v_mov_b32_e32 v134, 0
	v_mbcnt_hi_u32_b32 v153, -1, v2
	s_and_b64 vcc, exec, s[58:59]
	s_cbranch_vccz .Lb1db_p1_a
	s_barrier
.Lb1db_p1_a:
	ds_read_b128 v[240:243], v151
	ds_read_b128 v[244:247], v151 offset:1024
	ds_read_b128 v[248:251], v151 offset:2048
	ds_read_b128 v[252:255], v151 offset:3072
	s_waitcnt lgkmcnt(0)
	s_barrier
	s_cbranch_vccnz .Lb1db_p1_b
	s_barrier
.Lb1db_p1_b:
	s_waitcnt vmcnt(0)
	s_branch .LBB0_310

; #define PG8_STAGE(bufoff, gbase, voff) do { const char* _gb = (const char*)(gbase); asm volatile("" : "+s"(_gb)); _Pragma("unroll") for (int _i = 0; _i < 2; ++_i) { asm volatile("" : "+v"((voff)[_i])); \
;         __builtin_amdgcn_global_load_lds((const unsigned*)(_gb + (voff)[_i]), (PG8_LAS unsigned*)(lds + (bufoff) + ldsw + _i * 8192), 16, 0, 0); } } while (0)
; #define PG8_LDA(dst, b, h) do { _Pragma("unroll") for (int m = 0; m < 4; ++m) _Pragma("unroll") for (int k = 0; k < 2; ++k) dst[m][k] = *(const PG8_LAS bf16x8*)(lds + PG8_SA(b, h) + aoff + m * 2048 + k * 1024); } while (0)
; #define PG8_LDB(dst, b, h) do { _Pragma("unroll") for (int n = 0; n < 2; ++n) _Pragma("unroll") for (int k = 0; k < 2; ++k) dst[n][k] = *(const PG8_LAS bf16x8*)(lds + PG8_SB(b, h) + boff + n * 2048 + k * 1024); } while (0)
; #define PG8_WAIT_V(n) asm volatile("s_waitcnt vmcnt(" #n ")" ::: "memory")
; #define PG8_WAIT_L(n) asm volatile("s_waitcnt lgkmcnt(" #n ")" ::: "memory")
; #define PG8_BAR __builtin_amdgcn_s_barrier()
; #define PG8_SCHED __builtin_amdgcn_sched_barrier(0)
; #define PG8_STAGE(bufoff, gbase, voff) do { const char* _gb = (const char*)(gbase); asm volatile("" : "+s"(_gb)); _Pragma("unroll") for (int _i = 0; _i < 2; ++_i) { asm volatile("" : "+v"((voff)[_i])); \
;         __builtin_amdgcn_global_load_lds((const unsigned*)(_gb + (voff)[_i]), (PG8_LAS unsigned*)(lds + (bufoff) + ldsw + _i * 8192), 16, 0, 0); } } while (0)
; #define PG8_LDA(dst, b, h) do { _Pragma("unroll") for (int m = 0; m < 4; ++m) _Pragma("unroll") for (int k = 0; k < 2; ++k) dst[m][k] = *(const PG8_LAS bf16x8*)(lds + PG8_SA(b, h) + aoff + m * 2048 + k * 1024); } while (0)
; #define PG8_WAIT_V(n) asm volatile("s_waitcnt vmcnt(" #n ")" ::: "memory")
; template <class Epi, class Sched, bool ALIGN_EPI = false, bool SP2 = false>
; __device__ __forceinline__ void gemm_phase(PG8_LAS unsigned char* lds, const Gemm g, const Sched& S, const Epi& E) {
;     ...
;             PG8_LDB(B0, 0, 0); PG8_LDB(B1, 0, 1); PG8_SCHED; PG8_LDA(At, 0, 0); PG8_STAGE(PG8_SA(1, 1), a1 + hstep, voffA);
;             PG8_WAIT_V(8); PG8_WAIT_L(0); PG8_BAR; PG8_MMA2(0); PG8_BAR; PG8_SCHED;
;             PG8_LDA(At, 0, 1); PG8_STAGE(PG8_SB(0, 0), b2, voffB); PG8_STAGE(PG8_SB(0, 1), b2 + hstep, voffB); PG8_STAGE(PG8_SA(0, 0), a2, voffA);
;             PG8_WAIT_V(8); PG8_WAIT_L(0); PG8_BAR; PG8_MMA2(1); PG8_BAR; PG8_SCHED;
.LBB0_313:
	ds_read_b128 v[136:139], v150
	ds_read_b128 v[140:143], v150 offset:1024
	ds_read_b128 v[154:157], v150 offset:2048
	ds_read_b128 v[158:161], v150 offset:3072
	s_add_u32 s14, s8, 0x100
	s_addc_u32 s15, s9, 0
	s_cmp_eq_u32 s43, 60
	s_cselect_b32 s24, s13, s14
	s_cselect_b32 s25, s11, s15
	s_cselect_b32 s16, s36, s37
	s_cselect_b32 s17, s33, s42
	s_add_u32 s2, s24, 0x80
	s_addc_u32 s3, s25, 0
	s_add_u32 s8, s8, 0x100080
	s_addc_u32 s9, s9, 0
	s_add_i32 m0, s63, 0xc000
	ds_read_b128 v[178:181], v152
	ds_read_b128 v[182:185], v152 offset:1024
	ds_read_b128 v[186:189], v152 offset:2048
	ds_read_b128 v[190:193], v152 offset:3072
	ds_read_b128 v[194:197], v152 offset:4096
	ds_read_b128 v[198:201], v152 offset:5120
	ds_read_b128 v[202:205], v152 offset:6144
	ds_read_b128 v[206:209], v152 offset:7168
	s_nop 0
	global_load_lds_dwordx4 v1, s[8:9]
	s_add_i32 m0, s63, 0xe000
	s_nop 0
	global_load_lds_dwordx4 v145, s[8:9]
	s_add_u32 s8, s16, 0x100000
	s_addc_u32 s9, s17, 0
	s_add_i32 s44, s96, s61
	s_mov_b32 m0, s44
	s_nop 0
	global_load_lds_dwordx4 v144, s[8:9]
	s_add_i32 m0, s44, 0x2000
	s_nop 0
	global_load_lds_dwordx4 v146, s[8:9]
	s_waitcnt vmcnt(8)
	s_waitcnt lgkmcnt(0)
	s_setprio 1
	s_waitcnt lgkmcnt(0)
	s_barrier
	v_mfma_f32_16x16x32_bf16 v[126:129], v[136:139], v[178:181], v[126:129]
	v_mfma_f32_16x16x32_bf16 v[122:125], v[154:157], v[178:181], v[122:125]
	v_mfma_f32_16x16x32_bf16 v[110:113], v[136:139], v[186:189], v[110:113]
	v_mfma_f32_16x16x32_bf16 v[106:109], v[154:157], v[186:189], v[106:109]
	v_mfma_f32_16x16x32_bf16 v[94:97], v[136:139], v[194:197], v[94:97]
	v_mfma_f32_16x16x32_bf16 v[90:93], v[154:157], v[194:197], v[90:93]
	v_mfma_f32_16x16x32_bf16 v[78:81], v[136:139], v[202:205], v[78:81]
	v_mfma_f32_16x16x32_bf16 v[74:77], v[154:157], v[202:205], v[74:77]
	v_mfma_f32_16x16x32_bf16 v[118:121], v[240:243], v[178:181], v[118:121]
	v_mfma_f32_16x16x32_bf16 v[114:117], v[248:251], v[178:181], v[114:117]
	v_mfma_f32_16x16x32_bf16 v[102:105], v[240:243], v[186:189], v[102:105]
	v_mfma_f32_16x16x32_bf16 v[98:101], v[248:251], v[186:189], v[98:101]
	v_mfma_f32_16x16x32_bf16 v[86:89], v[240:243], v[194:197], v[86:89]
	v_mfma_f32_16x16x32_bf16 v[82:85], v[248:251], v[194:197], v[82:85]
	v_mfma_f32_16x16x32_bf16 v[70:73], v[240:243], v[202:205], v[70:73]
	v_mfma_f32_16x16x32_bf16 v[66:69], v[248:251], v[202:205], v[66:69]
	v_mfma_f32_16x16x32_bf16 v[126:129], v[140:143], v[182:185], v[126:129]
	v_mfma_f32_16x16x32_bf16 v[122:125], v[158:161], v[182:185], v[122:125]
	v_mfma_f32_16x16x32_bf16 v[110:113], v[140:143], v[190:193], v[110:113]
	v_mfma_f32_16x16x32_bf16 v[106:109], v[158:161], v[190:193], v[106:109]
	v_mfma_f32_16x16x32_bf16 v[94:97], v[140:143], v[198:201], v[94:97]
	v_mfma_f32_16x16x32_bf16 v[90:93], v[158:161], v[198:201], v[90:93]
	v_mfma_f32_16x16x32_bf16 v[78:81], v[140:143], v[206:209], v[78:81]
	v_mfma_f32_16x16x32_bf16 v[74:77], v[158:161], v[206:209], v[74:77]
	v_mfma_f32_16x16x32_bf16 v[118:121], v[244:247], v[182:185], v[118:121]
	v_mfma_f32_16x16x32_bf16 v[114:117], v[252:255], v[182:185], v[114:117]
	v_mfma_f32_16x16x32_bf16 v[102:105], v[244:247], v[190:193], v[102:105]
	v_mfma_f32_16x16x32_bf16 v[98:101], v[252:255], v[190:193], v[98:101]
	v_mfma_f32_16x16x32_bf16 v[86:89], v[244:247], v[198:201], v[86:89]
	v_mfma_f32_16x16x32_bf16 v[82:85], v[252:255], v[198:201], v[82:85]
	v_mfma_f32_16x16x32_bf16 v[70:73], v[244:247], v[206:209], v[70:73]
	v_mfma_f32_16x16x32_bf16 v[66:69], v[252:255], v[206:209], v[66:69]
	s_setprio 0
	s_barrier
	s_add_i32 s44, s95, s61
	s_mov_b64 s[8:9], s[16:17]
	s_mov_b32 m0, s44
	ds_read_b128 v[178:181], v152 offset:16384
	ds_read_b128 v[182:185], v152 offset:17408
	ds_read_b128 v[186:189], v152 offset:18432
	ds_read_b128 v[190:193], v152 offset:19456
	ds_read_b128 v[194:197], v152 offset:20480
	ds_read_b128 v[198:201], v152 offset:21504
	ds_read_b128 v[202:205], v152 offset:22528
	ds_read_b128 v[206:209], v152 offset:23552
	v_add_u32_e32 v239, 0x1c000, v148
	ds_read_b128 v[162:165], v239
	ds_read_b128 v[166:169], v239 offset:1024
	ds_read_b128 v[170:173], v239 offset:2048
	ds_read_b128 v[174:177], v239 offset:3072
	s_nop 0
	global_load_lds_dwordx4 v144, s[8:9]
	s_add_i32 m0, s44, 0x2000
	s_nop 0
	global_load_lds_dwordx4 v146, s[8:9]
	s_mov_b64 s[8:9], s[24:25]
	s_mov_b32 m0, s63
	s_nop 0
	global_load_lds_dwordx4 v1, s[8:9]
	s_mov_b32 m0, s65
	s_nop 0
	global_load_lds_dwordx4 v145, s[8:9]
	s_waitcnt vmcnt(8)
	s_waitcnt lgkmcnt(0)
	s_setprio 1
	s_waitcnt lgkmcnt(0)
	s_barrier
	v_mfma_f32_16x16x32_bf16 v[62:65], v[136:139], v[178:181], v[62:65]
	v_mfma_f32_16x16x32_bf16 v[58:61], v[154:157], v[178:181], v[58:61]
	v_mfma_f32_16x16x32_bf16 v[46:49], v[136:139], v[186:189], v[46:49]
	v_mfma_f32_16x16x32_bf16 v[42:45], v[154:157], v[186:189], v[42:45]
	v_mfma_f32_16x16x32_bf16 v[30:33], v[136:139], v[194:197], v[30:33]
	v_mfma_f32_16x16x32_bf16 v[26:29], v[154:157], v[194:197], v[26:29]
	v_mfma_f32_16x16x32_bf16 v[14:17], v[136:139], v[202:205], v[14:17]
	v_mfma_f32_16x16x32_bf16 v[10:13], v[154:157], v[202:205], v[10:13]
	v_mfma_f32_16x16x32_bf16 v[54:57], v[240:243], v[178:181], v[54:57]
	v_mfma_f32_16x16x32_bf16 v[50:53], v[248:251], v[178:181], v[50:53]
	v_mfma_f32_16x16x32_bf16 v[38:41], v[240:243], v[186:189], v[38:41]
	v_mfma_f32_16x16x32_bf16 v[34:37], v[248:251], v[186:189], v[34:37]
	v_mfma_f32_16x16x32_bf16 v[22:25], v[240:243], v[194:197], v[22:25]
	v_mfma_f32_16x16x32_bf16 v[18:21], v[248:251], v[194:197], v[18:21]
	v_mfma_f32_16x16x32_bf16 v[6:9], v[240:243], v[202:205], v[6:9]
	v_mfma_f32_16x16x32_bf16 v[2:5], v[248:251], v[202:205], v[2:5]
	v_mfma_f32_16x16x32_bf16 v[62:65], v[140:143], v[182:185], v[62:65]
	v_mfma_f32_16x16x32_bf16 v[58:61], v[158:161], v[182:185], v[58:61]
	v_mfma_f32_16x16x32_bf16 v[46:49], v[140:143], v[190:193], v[46:49]
	v_mfma_f32_16x16x32_bf16 v[42:45], v[158:161], v[190:193], v[42:45]
	v_mfma_f32_16x16x32_bf16 v[30:33], v[140:143], v[198:201], v[30:33]
	v_mfma_f32_16x16x32_bf16 v[26:29], v[158:161], v[198:201], v[26:29]
	v_mfma_f32_16x16x32_bf16 v[14:17], v[140:143], v[206:209], v[14:17]
	v_mfma_f32_16x16x32_bf16 v[10:13], v[158:161], v[206:209], v[10:13]
	v_mfma_f32_16x16x32_bf16 v[54:57], v[244:247], v[182:185], v[54:57]
	v_mfma_f32_16x16x32_bf16 v[50:53], v[252:255], v[182:185], v[50:53]
	v_mfma_f32_16x16x32_bf16 v[38:41], v[244:247], v[190:193], v[38:41]
	v_mfma_f32_16x16x32_bf16 v[34:37], v[252:255], v[190:193], v[34:37]
	v_mfma_f32_16x16x32_bf16 v[22:25], v[244:247], v[198:201], v[22:25]
	v_mfma_f32_16x16x32_bf16 v[18:21], v[252:255], v[198:201], v[18:21]
	v_mfma_f32_16x16x32_bf16 v[6:9], v[244:247], v[206:209], v[6:9]
	v_mfma_f32_16x16x32_bf16 v[2:5], v[252:255], v[206:209], v[2:5]
	s_setprio 0
	s_barrier
; #define PG8_STAGE(bufoff, gbase, voff) do { const char* _gb = (const char*)(gbase); asm volatile("" : "+s"(_gb)); _Pragma("unroll") for (int _i = 0; _i < 2; ++_i) { asm volatile("" : "+v"((voff)[_i])); \
;         __builtin_amdgcn_global_load_lds((const unsigned*)(_gb + (voff)[_i]), (PG8_LAS unsigned*)(lds + (bufoff) + ldsw + _i * 8192), 16, 0, 0); } } while (0)
; #define PG8_LDA(dst, b, h) do { _Pragma("unroll") for (int m = 0; m < 4; ++m) _Pragma("unroll") for (int k = 0; k < 2; ++k) dst[m][k] = *(const PG8_LAS bf16x8*)(lds + PG8_SA(b, h) + aoff + m * 2048 + k * 1024); } while (0)
; #define PG8_LDB(dst, b, h) do { _Pragma("unroll") for (int n = 0; n < 2; ++n) _Pragma("unroll") for (int k = 0; k < 2; ++k) dst[n][k] = *(const PG8_LAS bf16x8*)(lds + PG8_SB(b, h) + boff + n * 2048 + k * 1024); } while (0)
; #define PG8_WAIT_V(n) asm volatile("s_waitcnt vmcnt(" #n ")" ::: "memory")
; #define PG8_WAIT_L(n) asm volatile("s_waitcnt lgkmcnt(" #n ")" ::: "memory")
; #define PG8_BAR __builtin_amdgcn_s_barrier()
; #define PG8_SCHED __builtin_amdgcn_sched_barrier(0)
; #define PG8_STAGE(bufoff, gbase, voff) do { const char* _gb = (const char*)(gbase); asm volatile("" : "+s"(_gb)); _Pragma("unroll") for (int _i = 0; _i < 2; ++_i) { asm volatile("" : "+v"((voff)[_i])); \
;         __builtin_amdgcn_global_load_lds((const unsigned*)(_gb + (voff)[_i]), (PG8_LAS unsigned*)(lds + (bufoff) + ldsw + _i * 8192), 16, 0, 0); } } while (0)
; #define PG8_LDA(dst, b, h) do { _Pragma("unroll") for (int m = 0; m < 4; ++m) _Pragma("unroll") for (int k = 0; k < 2; ++k) dst[m][k] = *(const PG8_LAS bf16x8*)(lds + PG8_SA(b, h) + aoff + m * 2048 + k * 1024); } while (0)
; template <class Epi, class Sched, bool ALIGN_EPI = false, bool SP2 = false>
; __device__ __forceinline__ void gemm_phase(PG8_LAS unsigned char* lds, const Gemm g, const Sched& S, const Epi& E) {
;     ...
;             PG8_LDB(B0, 1, 0); PG8_LDB(B1, 1, 1); PG8_SCHED; PG8_LDA(At, 1, 0); PG8_STAGE(PG8_SA(0, 1), a2 + hstep, voffA);
;             PG8_WAIT_V(8); PG8_WAIT_L(0); PG8_BAR; PG8_MMA2(0); PG8_BAR; PG8_SCHED;
;             PG8_LDA(At, 1, 1); PG8_STAGE(PG8_SB(1, 0), b3, voffB); PG8_STAGE(PG8_SB(1, 1), b3 + hstep, voffB); PG8_STAGE(PG8_SA(1, 0), a3, voffA);
;             PG8_WAIT_V(8); PG8_WAIT_L(0); PG8_BAR; PG8_MMA2(1); PG8_BAR; PG8_SCHED;
;     ...
;         if constexpr (ALIGN_EPI) { if (wr == 0) PG8_BAR; }
	s_add_i32 s44, 0, 0x18000
	v_add_u32_e32 v135, s44, v148
	s_add_i32 s45, 0, 0x1c000
	ds_read_b128 v[136:139], v135
	ds_read_b128 v[140:143], v135 offset:1024
	ds_read_b128 v[154:157], v135 offset:2048
	ds_read_b128 v[158:161], v135 offset:3072
	s_add_u32 s8, s24, 0x100000
	s_addc_u32 s9, s25, 0
	s_mov_b32 m0, s88
	ds_read_b128 v[178:181], v152 offset:32768
	ds_read_b128 v[182:185], v152 offset:33792
	ds_read_b128 v[186:189], v152 offset:34816
	ds_read_b128 v[190:193], v152 offset:35840
	ds_read_b128 v[194:197], v152 offset:36864
	ds_read_b128 v[198:201], v152 offset:37888
	ds_read_b128 v[202:205], v152 offset:38912
	ds_read_b128 v[206:209], v152 offset:39936
	s_nop 0
	global_load_lds_dwordx4 v1, s[8:9]
	s_mov_b32 m0, s89
	s_nop 0
	global_load_lds_dwordx4 v145, s[8:9]
	s_add_u32 s8, s16, 0x100080
	s_addc_u32 s9, s17, 0
	s_add_i32 s98, s45, s61
	s_mov_b32 m0, s98
	s_nop 0
	global_load_lds_dwordx4 v144, s[8:9]
	s_add_i32 m0, s98, 0x2000
	s_nop 0
	global_load_lds_dwordx4 v146, s[8:9]
	s_waitcnt vmcnt(8)
	s_waitcnt lgkmcnt(0)
	s_setprio 1
	s_waitcnt lgkmcnt(0)
	s_barrier
	v_mfma_f32_16x16x32_bf16 v[126:129], v[136:139], v[178:181], v[126:129]
	v_mfma_f32_16x16x32_bf16 v[122:125], v[154:157], v[178:181], v[122:125]
	v_mfma_f32_16x16x32_bf16 v[110:113], v[136:139], v[186:189], v[110:113]
	v_mfma_f32_16x16x32_bf16 v[106:109], v[154:157], v[186:189], v[106:109]
	v_mfma_f32_16x16x32_bf16 v[94:97], v[136:139], v[194:197], v[94:97]
	v_mfma_f32_16x16x32_bf16 v[90:93], v[154:157], v[194:197], v[90:93]
	v_mfma_f32_16x16x32_bf16 v[78:81], v[136:139], v[202:205], v[78:81]
	v_mfma_f32_16x16x32_bf16 v[74:77], v[154:157], v[202:205], v[74:77]
	v_mfma_f32_16x16x32_bf16 v[118:121], v[162:165], v[178:181], v[118:121]
	v_mfma_f32_16x16x32_bf16 v[114:117], v[170:173], v[178:181], v[114:117]
	v_mfma_f32_16x16x32_bf16 v[102:105], v[162:165], v[186:189], v[102:105]
	v_mfma_f32_16x16x32_bf16 v[98:101], v[170:173], v[186:189], v[98:101]
	v_mfma_f32_16x16x32_bf16 v[86:89], v[162:165], v[194:197], v[86:89]
	v_mfma_f32_16x16x32_bf16 v[82:85], v[170:173], v[194:197], v[82:85]
	v_mfma_f32_16x16x32_bf16 v[70:73], v[162:165], v[202:205], v[70:73]
	v_mfma_f32_16x16x32_bf16 v[66:69], v[170:173], v[202:205], v[66:69]
	v_mfma_f32_16x16x32_bf16 v[126:129], v[140:143], v[182:185], v[126:129]
	v_mfma_f32_16x16x32_bf16 v[122:125], v[158:161], v[182:185], v[122:125]
	v_mfma_f32_16x16x32_bf16 v[110:113], v[140:143], v[190:193], v[110:113]
	v_mfma_f32_16x16x32_bf16 v[106:109], v[158:161], v[190:193], v[106:109]
	v_mfma_f32_16x16x32_bf16 v[94:97], v[140:143], v[198:201], v[94:97]
	v_mfma_f32_16x16x32_bf16 v[90:93], v[158:161], v[198:201], v[90:93]
	v_mfma_f32_16x16x32_bf16 v[78:81], v[140:143], v[206:209], v[78:81]
	v_mfma_f32_16x16x32_bf16 v[74:77], v[158:161], v[206:209], v[74:77]
	v_mfma_f32_16x16x32_bf16 v[118:121], v[166:169], v[182:185], v[118:121]
	v_mfma_f32_16x16x32_bf16 v[114:117], v[174:177], v[182:185], v[114:117]
	v_mfma_f32_16x16x32_bf16 v[102:105], v[166:169], v[190:193], v[102:105]
	v_mfma_f32_16x16x32_bf16 v[98:101], v[174:177], v[190:193], v[98:101]
	v_mfma_f32_16x16x32_bf16 v[86:89], v[166:169], v[198:201], v[86:89]
	v_mfma_f32_16x16x32_bf16 v[82:85], v[174:177], v[198:201], v[82:85]
	v_mfma_f32_16x16x32_bf16 v[70:73], v[166:169], v[206:209], v[70:73]
	v_mfma_f32_16x16x32_bf16 v[66:69], v[174:177], v[206:209], v[66:69]
	s_setprio 0
	s_barrier
	s_add_u32 s8, s16, 0x80
	s_addc_u32 s9, s17, 0
	s_add_i32 s24, s44, s61
	s_mov_b32 m0, s24
	ds_read_b128 v[178:181], v152 offset:49152
	ds_read_b128 v[182:185], v152 offset:50176
	ds_read_b128 v[186:189], v152 offset:51200
	ds_read_b128 v[190:193], v152 offset:52224
	ds_read_b128 v[194:197], v152 offset:53248
	ds_read_b128 v[198:201], v152 offset:54272
	ds_read_b128 v[202:205], v152 offset:55296
	ds_read_b128 v[206:209], v152 offset:56320
	ds_read_b128 v[240:243], v151
	ds_read_b128 v[244:247], v151 offset:1024
	ds_read_b128 v[248:251], v151 offset:2048
	ds_read_b128 v[252:255], v151 offset:3072
	s_nop 0
	global_load_lds_dwordx4 v144, s[8:9]
	s_add_i32 m0, s24, 0x2000
	s_nop 0
	global_load_lds_dwordx4 v146, s[8:9]
	s_add_i32 s16, s45, s61
	s_mov_b32 m0, s91
	s_nop 0
	global_load_lds_dwordx4 v1, s[2:3]
	s_mov_b32 m0, s92
	s_nop 0
	global_load_lds_dwordx4 v145, s[2:3]
	s_waitcnt vmcnt(8)
	s_waitcnt lgkmcnt(0)
	s_setprio 1
	s_waitcnt lgkmcnt(0)
	s_barrier
	v_mfma_f32_16x16x32_bf16 v[62:65], v[136:139], v[178:181], v[62:65]
	v_mfma_f32_16x16x32_bf16 v[58:61], v[154:157], v[178:181], v[58:61]
	v_mfma_f32_16x16x32_bf16 v[46:49], v[136:139], v[186:189], v[46:49]
	v_mfma_f32_16x16x32_bf16 v[42:45], v[154:157], v[186:189], v[42:45]
	v_mfma_f32_16x16x32_bf16 v[30:33], v[136:139], v[194:197], v[30:33]
	v_mfma_f32_16x16x32_bf16 v[26:29], v[154:157], v[194:197], v[26:29]
	v_mfma_f32_16x16x32_bf16 v[14:17], v[136:139], v[202:205], v[14:17]
	v_mfma_f32_16x16x32_bf16 v[10:13], v[154:157], v[202:205], v[10:13]
	v_mfma_f32_16x16x32_bf16 v[54:57], v[162:165], v[178:181], v[54:57]
	v_mfma_f32_16x16x32_bf16 v[50:53], v[170:173], v[178:181], v[50:53]
	v_mfma_f32_16x16x32_bf16 v[38:41], v[162:165], v[186:189], v[38:41]
	v_mfma_f32_16x16x32_bf16 v[34:37], v[170:173], v[186:189], v[34:37]
	v_mfma_f32_16x16x32_bf16 v[22:25], v[162:165], v[194:197], v[22:25]
	v_mfma_f32_16x16x32_bf16 v[18:21], v[170:173], v[194:197], v[18:21]
	v_mfma_f32_16x16x32_bf16 v[6:9], v[162:165], v[202:205], v[6:9]
	v_mfma_f32_16x16x32_bf16 v[2:5], v[170:173], v[202:205], v[2:5]
	v_mfma_f32_16x16x32_bf16 v[62:65], v[140:143], v[182:185], v[62:65]
	v_mfma_f32_16x16x32_bf16 v[58:61], v[158:161], v[182:185], v[58:61]
	v_mfma_f32_16x16x32_bf16 v[46:49], v[140:143], v[190:193], v[46:49]
	v_mfma_f32_16x16x32_bf16 v[42:45], v[158:161], v[190:193], v[42:45]
	v_mfma_f32_16x16x32_bf16 v[30:33], v[140:143], v[198:201], v[30:33]
	v_mfma_f32_16x16x32_bf16 v[26:29], v[158:161], v[198:201], v[26:29]
	v_mfma_f32_16x16x32_bf16 v[14:17], v[140:143], v[206:209], v[14:17]
	v_mfma_f32_16x16x32_bf16 v[10:13], v[158:161], v[206:209], v[10:13]
	v_mfma_f32_16x16x32_bf16 v[54:57], v[166:169], v[182:185], v[54:57]
	v_mfma_f32_16x16x32_bf16 v[50:53], v[174:177], v[182:185], v[50:53]
	v_mfma_f32_16x16x32_bf16 v[38:41], v[166:169], v[190:193], v[38:41]
	v_mfma_f32_16x16x32_bf16 v[34:37], v[174:177], v[190:193], v[34:37]
	v_mfma_f32_16x16x32_bf16 v[22:25], v[166:169], v[198:201], v[22:25]
	v_mfma_f32_16x16x32_bf16 v[18:21], v[174:177], v[198:201], v[18:21]
	v_mfma_f32_16x16x32_bf16 v[6:9], v[166:169], v[206:209], v[6:9]
	v_mfma_f32_16x16x32_bf16 v[2:5], v[174:177], v[206:209], v[2:5]
	s_setprio 0
	s_barrier
	s_add_i32 s43, s43, 2
	s_add_u32 s37, s37, 0x100
	s_addc_u32 s42, s42, 0
	s_cmp_gt_u32 s43, 61
	s_mov_b64 s[8:9], s[14:15]
	s_cbranch_scc0 .LBB0_313
	s_and_b64 vcc, exec, s[58:59]
	s_cbranch_vccz .LBB0_333
	s_barrier
	s_cmp_lt_i32 s12, 24
	s_cbranch_scc0 .LBB0_334
